# attn_prompt key-pair loop: bf16 pack by v_cvt_pk_bf16_f32, V transpose reads issued at the top of the iteration
# speedup vs baseline: 1.0139x; 1.0088x over previous
; #define LAS __attribute__((address_space(3)))
; __device__ __forceinline__ void attn_prompt(const Params& p, int j, LAS unsigned char* lds, const int wave, const int lane) {
;     ...
;         for (int kp = kp0; kp < 5; ++kp) {
;             const int kbase = q0 - 144 + 32 * kp, lrow = 16 * wave + 32 * kp;
;             f32x4 st[2];
; #pragma unroll
;             for (int tl = 0; tl < 2; ++tl) {
;                 const LAS unsigned char* kr = Kl + (lrow + tl * 16 + fr) * 144 + g4 * 16;
;                 const bf16x8 kf0 = *(const LAS bf16x8*)kr, kf1 = *(const LAS bf16x8*)(kr + 64);
;                 f32x4 sv = (f32x4){0.f, 0.f, 0.f, 0.f};
;                 sv = __builtin_amdgcn_mfma_f32_16x16x32_bf16(kf0, qf0, sv, 0, 0, 0);
;                 sv = __builtin_amdgcn_mfma_f32_16x16x32_bf16(kf1, qf1, sv, 0, 0, 0);
;                 st[tl] = sv;
;             }
;             float mx = -1e30f; bool val[2][4];
; #pragma unroll
;             for (int tl = 0; tl < 2; ++tl)
; #pragma unroll
;                 for (int e = 0; e < 4; ++e) { const int uk = kbase + tl * 16 + g4 * 4 + e, dist = uq - uk; val[tl][e] = (uk >= 0) && (dist >= 0) && (dist <= 128);
;                     st[tl][e] = val[tl][e] ? st[tl][e] * 0.125f : -1e30f; mx = fmaxf(mx, st[tl][e]); }
;             mx = xmax4(mx);
;             const float mnew = fmaxf(mrun, mx), sc = __expf(mrun - mnew);
;             mrun = mnew; lrun *= sc;
; #pragma unroll
;             for (int dt = 0; dt < 4; ++dt) acc[dt] = acc[dt] * sc;
;             float pv[2][4];
; #pragma unroll
;             for (int tl = 0; tl < 2; ++tl)
; #pragma unroll
;                 for (int e = 0; e < 4; ++e) { pv[tl][e] = val[tl][e] ? __expf(st[tl][e] - mnew) : 0.f; lrun += pv[tl][e]; }
;             bf16x8 pf;
;             { u32x4 w; w.x = pk2(pv[0][0], pv[0][1]); w.y = pk2(pv[0][2], pv[0][3]); w.z = pk2(pv[1][0], pv[1][1]); w.w = pk2(pv[1][2], pv[1][3]); pf = __builtin_bit_cast(bf16x8, w); }
; #pragma unroll
;             for (int dt = 0; dt < 4; ++dt) {
;                 LAS unsigned char* ta = Vl + (lrow + g4 * 4 + (fr >> 2)) * 136 + dt * 32 + 8 * (fr & 3);
;                 const s16x4_ lo = __builtin_amdgcn_ds_read_tr16_b64_v4i16((LAS s16x4_*)ta), hi = __builtin_amdgcn_ds_read_tr16_b64_v4i16((LAS s16x4_*)(ta + 2176));
;                 const bf16x8 vf = (bf16x8){lo[0], lo[1], lo[2], lo[3], hi[0], hi[1], hi[2], hi[3]};
.LBB0_313:
	ds_read_b64_tr_b16 v[120:121], v86 offset:39424
	ds_read_b64_tr_b16 v[122:123], v86 offset:41600
	ds_read_b64_tr_b16 v[124:125], v86 offset:39456
	ds_read_b64_tr_b16 v[126:127], v86 offset:41632
	ds_read_b64_tr_b16 v[128:129], v86 offset:39488
	ds_read_b64_tr_b16 v[130:131], v86 offset:41664
	ds_read_b64_tr_b16 v[132:133], v86 offset:39520
	ds_read_b64_tr_b16 v[134:135], v86 offset:41696
	v_add_u32_e32 v74, 0, v84
	ds_read_b128 v[108:111], v74
	ds_read_b128 v[112:115], v74 offset:64
	v_mov_b32_e32 v73, v85
	v_add_u32_e32 v85, 17, v81
	v_cmp_lt_i32_e64 s[52:53], -1, v83
	s_waitcnt lgkmcnt(1)
	v_mfma_f32_16x16x32_bf16 v[108:111], v[108:111], v[40:43], 0
	v_cmp_gt_u32_e64 s[50:51], s35, v85
	s_and_b64 s[50:51], s[52:53], s[50:51]
	s_movk_i32 s26, 0xff7e
	s_waitcnt lgkmcnt(0)
	v_mfma_f32_16x16x32_bf16 v[108:111], v[112:115], v[44:47], v[108:111]
	ds_read_b128 v[112:115], v74 offset:2304
	ds_read_b128 v[116:119], v74 offset:2368
	v_add_u32_e32 v74, 19, v81
	v_cmp_gt_u32_e32 vcc, s35, v74
	s_waitcnt lgkmcnt(1)
	v_mfma_f32_16x16x32_bf16 v[112:115], v[112:115], v[40:43], 0
	s_nop 1
	v_mul_f32_e32 v85, 0x3e000000, v110
	v_mul_f32_e32 v74, 0x3e000000, v108
	v_cndmask_b32_e64 v108, v221, v85, s[50:51]
	v_add_u32_e32 v85, 16, v81
	v_cmp_lt_u32_e64 s[48:49], s26, v107
	v_cmp_gt_u32_e64 s[54:55], s35, v85
	s_waitcnt lgkmcnt(0)
	v_mfma_f32_16x16x32_bf16 v[112:115], v[116:119], v[44:47], v[112:115]
	s_and_b64 vcc, s[52:53], vcc
	s_and_b64 s[48:49], s[52:53], s[48:49]
	s_and_b64 s[52:53], s[52:53], s[54:55]
	v_mul_f32_e32 v85, 0x3e000000, v111
	v_cndmask_b32_e32 v75, v221, v74, vcc
	v_mul_f32_e32 v74, 0x3e000000, v109
	v_cndmask_b32_e64 v109, v221, v85, s[52:53]
	v_add_u32_e32 v85, 16, v83
	v_cmp_lt_i32_e64 s[58:59], -1, v85
	v_add_u32_e32 v85, 3, v81
	v_cmp_gt_u32_e64 s[54:55], s35, v85
	s_and_b64 s[54:55], s[58:59], s[54:55]
	v_mul_f32_e32 v85, 0x3e000000, v112
	v_cndmask_b32_e64 v110, v221, v85, s[54:55]
	v_add_u32_e32 v85, 2, v81
	v_cmp_gt_u32_e64 s[60:61], s35, v85
	s_and_b64 s[60:61], s[58:59], s[60:61]
	v_mul_f32_e32 v85, 0x3e000000, v113
	v_cndmask_b32_e64 v111, v221, v85, s[60:61]
	v_add_u32_e32 v85, 1, v81
	v_cndmask_b32_e64 v87, v221, v74, s[48:49]
	s_mov_b32 s26, 0xf149f2ca
	v_cmp_gt_u32_e64 s[62:63], s35, v85
	v_max3_f32 v74, v75, s26, v87
	s_and_b64 s[62:63], s[58:59], s[62:63]
	v_mul_f32_e32 v85, 0x3e000000, v114
	v_cmp_gt_u32_e64 s[64:65], s35, v81
	v_max3_f32 v74, v74, v108, v109
	v_cndmask_b32_e64 v112, v221, v85, s[62:63]
	s_and_b64 s[58:59], s[58:59], s[64:65]
	v_mul_f32_e32 v85, 0x3e000000, v115
	v_max3_f32 v74, v74, v110, v111
	v_cndmask_b32_e64 v113, v221, v85, s[58:59]
	v_max3_f32 v74, v74, v112, v113
	v_mov_b32_e32 v85, v74
	s_nop 1
	v_permlane16_swap_b32 v74, v85
	s_add_i32 s25, s25, 1
	v_max_f32_e32 v85, v85, v85
	v_max_f32_e32 v74, v74, v74
	v_max_f32_e32 v74, v74, v85
	v_mov_b32_e32 v85, v74
	s_nop 1
	v_permlane32_swap_b32 v74, v85
	v_subrev_u32_e32 v81, 32, v81
	v_max3_f32 v85, v73, v74, v85
	v_sub_f32_e32 v73, v73, v85
	v_mul_f32_e32 v73, 0x3fb8aa3b, v73
	v_exp_f32_e32 v74, v73
	v_sub_f32_e32 v73, v75, v85
	v_mul_f32_e32 v73, 0x3fb8aa3b, v73
	v_exp_f32_e32 v73, v73
	v_pk_mul_f32 v[70:71], v[70:71], v[74:75] op_sel_hi:[1,0]
	v_pk_mul_f32 v[68:69], v[68:69], v[74:75] op_sel_hi:[1,0]
	v_pk_mul_f32 v[66:67], v[66:67], v[74:75] op_sel_hi:[1,0]
	v_cndmask_b32_e32 v73, 0, v73, vcc
	v_pk_mul_f32 v[64:65], v[64:65], v[74:75] op_sel_hi:[1,0]
	v_pk_mul_f32 v[62:63], v[62:63], v[74:75] op_sel_hi:[1,0]
	v_pk_mul_f32 v[60:61], v[60:61], v[74:75] op_sel_hi:[1,0]
	v_pk_mul_f32 v[58:59], v[58:59], v[74:75] op_sel_hi:[1,0]
	v_pk_mul_f32 v[56:57], v[56:57], v[74:75] op_sel_hi:[1,0]
	v_fma_f32 v72, v72, v74, v73
	v_sub_f32_e32 v74, v87, v85
	v_mul_f32_e32 v74, 0x3fb8aa3b, v74
	v_sub_f32_e32 v75, v108, v85
	v_exp_f32_e32 v74, v74
	v_mul_f32_e32 v75, 0x3fb8aa3b, v75
	v_sub_f32_e32 v87, v109, v85
	v_exp_f32_e32 v75, v75
	v_mul_f32_e32 v87, 0x3fb8aa3b, v87
	v_sub_f32_e32 v108, v110, v85
	v_exp_f32_e32 v87, v87
	v_mul_f32_e32 v108, 0x3fb8aa3b, v108
	v_sub_f32_e32 v109, v111, v85
	v_exp_f32_e32 v108, v108
	v_mul_f32_e32 v109, 0x3fb8aa3b, v109
	v_sub_f32_e32 v110, v112, v85
	v_cndmask_b32_e64 v74, 0, v74, s[48:49]
	v_exp_f32_e32 v109, v109
	v_mul_f32_e32 v110, 0x3fb8aa3b, v110
	v_add_f32_e32 v72, v74, v72
	v_cndmask_b32_e64 v75, 0, v75, s[50:51]
	v_exp_f32_e32 v110, v110
	v_add_f32_e32 v72, v75, v72
	v_cndmask_b32_e64 v87, 0, v87, s[52:53]
	v_add_f32_e32 v72, v87, v72
	v_cndmask_b32_e64 v108, 0, v108, s[54:55]
	v_add_f32_e32 v72, v108, v72
	v_cndmask_b32_e64 v109, 0, v109, s[60:61]
	v_add_f32_e32 v72, v109, v72
	v_cndmask_b32_e64 v110, 0, v110, s[62:63]
	v_add_f32_e32 v116, v110, v72
	v_sub_f32_e32 v72, v113, v85
	v_mul_f32_e32 v72, 0x3fb8aa3b, v72
	v_exp_f32_e32 v72, v72
	v_add_u32_e32 v83, 32, v83
	v_add_u32_e32 v107, 32, v107
	v_add_u32_e32 v84, 0x1200, v84
	v_cndmask_b32_e64 v117, 0, v72, s[58:59]
	v_cvt_pk_bf16_f32 v72, v73, v74
	v_cvt_pk_bf16_f32 v73, v75, v87
	v_cvt_pk_bf16_f32 v74, v108, v109
	v_cvt_pk_bf16_f32 v75, v110, v117
	v_add_u32_e32 v86, 0x1100, v86
	s_cmp_gt_u32 s25, 3
	s_nop 0
	v_mfma_f32_16x16x32_bf16 v[68:71], v[120:123], v[72:75], v[68:71]
	v_mfma_f32_16x16x32_bf16 v[60:63], v[128:131], v[72:75], v[60:63]
	v_mfma_f32_16x16x32_bf16 v[64:67], v[124:127], v[72:75], v[64:67]
	v_mfma_f32_16x16x32_bf16 v[56:59], v[132:135], v[72:75], v[56:59]
	v_add_f32_e32 v72, v117, v116
	s_cbranch_scc0 .LBB0_313
	s_branch .LBB0_315
